# GLA output phase: half of the workgroups (bit 3 of blockIdx.x) start ~4.5K cycles late (pipeline fill/drain overlap)
# baseline (speedup 1.0000x reference)
; #define LAS __attribute__((address_space(3)))
; __device__ __forceinline__ void phase_gla_out(Frame& F) {
;     bf16_t* QKVR = (bf16_t*)(F.ws + WS_QKVR); const bf16_t* KVF = (const bf16_t*)(F.ws + WS_KVF); const float* gn = F.in[18];
;     const int tid = F.tid, lane = F.lane, w = F.wave, g = lane >> 4, li = lane & 15;
;     LAS float* red = (LAS float*)(F.lds + 32768);
;     constexpr int SLABP = NH * 16 * 4, NU = NB * (SEQ / CH) * NH;
;     int poff[2]; size_t gq[2];
; #pragma unroll
;     for (int i = 0; i < 2; ++i) { const int idx = tid + NTHR * i, row = idx >> 4, ch = idx & 15; poff[i] = img_off(row, ch); gq[i] = (size_t)row * NQKVR + ch * 8; }
;     ...
;     u32x4 sA[2][4], sB[2][4]; u32x4 rA[4], rB[4]; u32x4 qA[2], qB[2];
;     int un = F.bid;
;     if (un < NU) GO_LOAD(un, sA, rA, qA);
.LBB0_910:
	s_and_b32 s0, s92, 0x200
	s_mov_b32 s1, 0
	s_cmp_eq_u64 s[0:1], 0
	s_mov_b64 s[14:15], 0
	s_barrier
	s_cbranch_scc1 .LBB0_921
	s_bitcmp1_b32 s2, 3
	s_cbranch_scc0 .Lsp_910
	s_sleep 70
.Lsp_910:
	v_readlane_b32 s0, v252, 42
	v_readlane_b32 s1, v252, 43
	s_and_b64 vcc, exec, s[0:1]
	s_cbranch_vccnz .LBB0_920
	s_waitcnt vmcnt(11)
	v_mbcnt_lo_u32_b32 v0, -1, 0
	v_mbcnt_hi_u32_b32 v57, -1, v0
	s_and_b32 s0, s90, 0xffffffc0
	v_add_u32_e32 v0, s0, v57
	v_ashrrev_i32_e32 v62, 4, v0
	v_add_u32_e32 v0, 0x200, v0
	s_add_u32 s18, s34, 0x4000000
	s_movk_i32 s4, 0xc00
	v_ashrrev_i32_e32 v63, 4, v0
	s_addc_u32 s19, s35, 0
	v_and_b32_e32 v152, 15, v57
	v_mad_i64_i32 v[154:155], s[0:1], v62, s4, 0
	v_mad_i64_i32 v[156:157], s[0:1], v63, s4, 0
	s_and_b32 s12, s2, 3
	s_ashr_i32 s10, s2, 2
	v_lshlrev_b32_e32 v1, 3, v152
	s_ashr_i32 s11, s10, 31
	s_lshl_b32 s0, s3, 3
	v_lshlrev_b32_e32 v158, 4, v57
	v_mov_b32_e32 v159, 0
	s_lshl_b32 s1, s12, 6
	v_or_b32_e32 v154, v154, v1
	v_or_b32_e32 v156, v156, v1
	s_lshl_b64 s[4:5], s[10:11], 8
	v_lshl_add_u64 v[0:1], s[34:35], 0, v[158:159]
	s_mov_b64 s[6:7], 0xa000000
	s_add_i32 s1, s1, s0
	v_lshl_add_u64 v[160:161], v[0:1], 0, s[6:7]
	s_add_u32 s6, s4, s1
	s_addc_u32 s7, s5, 0
	s_lshl_b64 s[6:7], s[6:7], 10
	s_or_b32 s1, s1, 4
	s_add_u32 s4, s4, s1
	s_addc_u32 s5, s5, 0
	s_lshl_b64 s[4:5], s[4:5], 10
	v_lshl_add_u64 v[16:17], v[160:161], 0, s[6:7]
	v_lshl_add_u64 v[32:33], v[160:161], 0, s[4:5]
	s_lshl_b64 s[4:5], s[10:11], 6
	global_load_dwordx4 v[0:3], v[16:17], off
	global_load_dwordx4 v[4:7], v[16:17], off offset:1024
	global_load_dwordx4 v[8:11], v[16:17], off offset:2048
	global_load_dwordx4 v[12:15], v[16:17], off offset:3072
	s_nop 0
	global_load_dwordx4 v[16:19], v[32:33], off
	global_load_dwordx4 v[20:23], v[32:33], off offset:1024
	global_load_dwordx4 v[24:27], v[32:33], off offset:2048
	global_load_dwordx4 v[28:31], v[32:33], off offset:3072
	v_or_b32_e32 v34, s4, v152
	s_movk_i32 s1, 0x1800
	v_mov_b64_e32 v[32:33], s[18:19]
	s_mov_b32 s17, 0
	v_mad_u64_u32 v[32:33], s[6:7], v34, s1, v[32:33]
	v_mov_b32_e32 v153, 0x1800
	v_lshrrev_b32_e32 v64, 1, v57
	v_mad_i32_i24 v33, s5, v153, v33
	s_lshl_b32 s4, s12, 9
	s_mov_b32 s5, s17
	v_and_b32_e32 v56, 56, v64
	s_lshl_b32 s6, s3, 6
	s_mov_b32 s7, s17
	v_lshl_add_u64 v[32:33], v[32:33], 0, s[4:5]
	v_lshlrev_b32_e32 v158, 1, v56
	v_lshl_add_u64 v[32:33], v[32:33], 0, s[6:7]
	v_lshl_add_u64 v[40:41], v[32:33], 0, v[158:159]
	s_movk_i32 s4, 0x1000
	v_add_co_u32_e32 v42, vcc, s4, v40
	s_mov_b32 s5, 0x19000
	s_nop 0
	v_addc_co_u32_e32 v43, vcc, 0, v41, vcc
	s_lshl_b32 s11, s12, 8
	s_lshl_b32 s16, s3, 5
	v_add_co_u32_e32 v44, vcc, s5, v40
	s_mul_hi_i32 s12, s10, 0x60000
	s_mul_i32 s10, s10, 0x60000
	v_addc_co_u32_e32 v45, vcc, 0, v41, vcc
	s_mov_b32 s6, 0x31000
	s_add_u32 s10, s18, s10
	global_load_dwordx4 v[32:35], v[42:43], off
	global_load_dwordx4 v[36:39], v[44:45], off
	v_add_co_u32_e32 v42, vcc, s6, v40
	s_addc_u32 s12, s19, s12
	s_nop 0
	v_addc_co_u32_e32 v43, vcc, 0, v41, vcc
	s_mov_b32 s7, 0x49000
	s_add_u32 s10, s10, s11
	v_add_co_u32_e32 v44, vcc, s7, v40
	s_addc_u32 s11, s12, 0
	s_nop 0
	v_addc_co_u32_e32 v45, vcc, 0, v41, vcc
	v_lshl_add_u64 v[58:59], v[154:155], 1, s[10:11]
	global_load_dwordx4 v[40:43], v[42:43], off
	s_nop 0
	global_load_dwordx4 v[44:47], v[44:45], off
	v_lshl_add_u64 v[60:61], v[156:157], 1, s[10:11]
	global_load_dwordx4 v[48:51], v[58:59], off
	global_load_dwordx4 v[52:55], v[60:61], off
	v_lshlrev_b32_e32 v58, 2, v63
	v_and_b32_e32 v58, 12, v58
	v_bfe_u32 v59, v63, 2, 2
	v_readlane_b32 s36, v252, 18
	v_bitop3_b32 v58, v58, v152, v59 bitop3:0x36
	v_lshlrev_b32_e32 v59, 8, v63
	v_readlane_b32 s40, v252, 22
	v_readlane_b32 s41, v252, 23
	v_lshl_or_b32 v58, v58, 4, v59
	v_lshlrev_b32_e32 v59, 2, v62
	s_lshl_b64 s[10:11], s[16:17], 2
	s_mov_b64 s[12:13], s[40:41]
	v_and_b32_e32 v59, 12, v59
	v_bfe_u32 v60, v62, 2, 2
	s_add_u32 s10, s12, s10
	v_bitop3_b32 v59, v59, v152, v60 bitop3:0x36
	v_lshlrev_b32_e32 v60, 8, v62
	s_addc_u32 s11, s13, s11
	v_lshrrev_b32_e32 v62, 5, v57
	v_lshlrev_b32_e32 v65, 2, v152
	s_lshl_b32 s12, s3, 8
	v_lshl_or_b32 v59, v59, 4, v60
	v_lshlrev_b32_e32 v60, 2, v57
	v_lshlrev_b32_e32 v158, 2, v56
	v_and_b32_e32 v66, 12, v65
	v_bfe_u32 v67, v57, 2, 2
	v_add_u32_e32 v68, 2, v62
	s_add_i32 s13, s12, 0
	v_add_u32_e32 v61, 0, v60
	v_lshl_add_u64 v[162:163], s[10:11], 0, v[158:159]
	v_cmp_gt_u32_e64 s[10:11], 16, v57
	v_add_u32_e32 v165, s13, v60
	v_bitop3_b32 v57, v66, v62, v67 bitop3:0x36
	v_bitop3_b32 v60, v66, v68, v67 bitop3:0x36
	v_or_b32_e32 v68, 4, v62
	v_add_u32_e32 v69, 6, v62
	v_or_b32_e32 v70, 8, v62
	v_add_u32_e32 v71, 10, v62
	v_or_b32_e32 v72, 12, v62
	v_add_u32_e32 v62, 14, v62
	v_lshlrev_b32_e32 v63, 8, v152
	v_and_b32_e32 v64, 8, v64
	v_bitop3_b32 v68, v66, v68, v67 bitop3:0x36
	v_bitop3_b32 v69, v66, v69, v67 bitop3:0x36
	v_bitop3_b32 v70, v66, v70, v67 bitop3:0x36
	v_bitop3_b32 v71, v66, v71, v67 bitop3:0x36
	v_bitop3_b32 v72, v66, v72, v67 bitop3:0x36
	v_bitop3_b32 v62, v66, v62, v67 bitop3:0x36
	v_lshlrev_b32_e32 v57, 4, v57
	v_lshlrev_b32_e32 v60, 4, v60
	v_lshlrev_b32_e32 v68, 4, v68
	v_lshlrev_b32_e32 v69, 4, v69
	v_lshlrev_b32_e32 v70, 4, v70
	v_lshlrev_b32_e32 v71, 4, v71
	v_lshlrev_b32_e32 v72, 4, v72
	v_lshlrev_b32_e32 v62, 4, v62
	v_add3_u32 v63, 0, v64, v63
	v_add_u32_e32 v167, 0, v65
	v_or_b32_e32 v164, 16, v152
	v_or_b32_e32 v166, 32, v152
	v_or_b32_e32 v168, 48, v152
	s_lshl_b32 s26, s2, 8
	s_lshl_b32 s27, s33, 9
	s_lshl_b32 s28, s33, 1
	s_lshl_b32 s29, s33, 8
	v_lshlrev_b32_e32 v158, 1, v56
	v_add_u32_e32 v169, s12, v61
	v_mov_b32_e32 v170, 0x358637bd
	s_mov_b32 s30, 0xf800000
	v_mov_b32_e32 v171, 0x260
	s_lshl_b32 s16, s16, 1
	v_add_u32_e32 v172, 0, v59
	v_add_u32_e32 v173, 0, v58
	v_add_u32_e32 v174, v63, v57
	v_add_u32_e32 v175, v63, v60
	v_add_u32_e32 v176, v63, v68
	v_add_u32_e32 v177, v63, v69
	v_add_u32_e32 v178, v63, v70
	v_add_u32_e32 v179, v63, v71
	v_add_u32_e32 v180, v63, v72
	v_add_u32_e32 v181, v63, v62
	s_mov_b32 s36, s2
	v_readlane_b32 s37, v252, 19
	v_readlane_b32 s38, v252, 20
	v_readlane_b32 s39, v252, 21
	v_readlane_b32 s42, v252, 24
	v_readlane_b32 s43, v252, 25
	v_readlane_b32 s44, v252, 26
	v_readlane_b32 s45, v252, 27
	v_readlane_b32 s46, v252, 28
	v_readlane_b32 s47, v252, 29
	v_readlane_b32 s48, v252, 30
	v_readlane_b32 s49, v252, 31
	v_readlane_b32 s50, v252, 32
	v_readlane_b32 s51, v252, 33
	s_branch .LBB0_915
